# adaLN modulation GEMV: 16 weight loads in flight per wave with counted vmcnt (was one load per step with vmcnt(0)), first block issued before the silu(c) barrier
# speedup vs baseline: 1.0424x; 1.0185x over previous
.LBB0_113:
	s_or_b64 exec, exec, s[14:15]
	s_mul_hi_i32 s14, s34, 0x2aaaaaab
	s_lshr_b32 s15, s14, 31
	s_ashr_i32 s20, s14, 4
	s_add_i32 s20, s20, s15
	s_mul_i32 s14, s20, 0x60
	s_sub_i32 s14, s34, s14
	s_lshl_b32 s18, s14, 6
	s_ashr_i32 s19, s18, 31
	s_mul_i32 s16, s20, 0x1800000
	s_lshl_b64 s[14:15], s[18:19], 2
	s_mul_hi_i32 s17, s20, 0x1800000
	s_add_u32 s16, s16, s14
	s_addc_u32 s17, s17, s15
	v_mov_b32_e32 v78, 0
	v_lshl_add_u64 v[2:3], v[16:17], 0, s[16:17]
	v_lshl_add_u64 v[4:5], v[18:19], 0, s[16:17]
	v_lshl_add_u64 v[6:7], v[20:21], 0, s[16:17]
	v_lshl_add_u64 v[52:53], v[22:23], 0, s[16:17]
	v_lshl_add_u64 v[54:55], v[24:25], 0, s[16:17]
	v_lshl_add_u64 v[56:57], v[26:27], 0, s[16:17]
	v_lshl_add_u64 v[58:59], v[28:29], 0, s[16:17]
	v_lshl_add_u64 v[60:61], v[30:31], 0, s[16:17]
	v_lshl_add_u64 v[62:63], v[32:33], 0, s[16:17]
	v_lshl_add_u64 v[64:65], v[34:35], 0, s[16:17]
	v_lshl_add_u64 v[66:67], v[36:37], 0, s[16:17]
	v_lshl_add_u64 v[68:69], v[38:39], 0, s[16:17]
	v_lshl_add_u64 v[70:71], v[40:41], 0, s[16:17]
	v_lshl_add_u64 v[72:73], v[42:43], 0, s[16:17]
	v_lshl_add_u64 v[74:75], v[44:45], 0, s[16:17]
	v_lshl_add_u64 v[76:77], v[46:47], 0, s[16:17]
	s_mov_b64 s[88:89], 0
	v_mov_b32_e32 v10, v110
	v_mov_b32_e32 v82, 0
	v_mov_b32_e32 v80, 0
	v_mov_b32_e32 v86, 0
	v_mov_b32_e32 v84, 0
	v_mov_b32_e32 v90, 0
	v_mov_b32_e32 v88, 0
	v_mov_b32_e32 v92, 0
	v_mov_b32_e32 v94, 0
	v_mov_b32_e32 v79, v78
	v_mov_b32_e32 v83, v78
	v_mov_b32_e32 v81, v78
	v_mov_b32_e32 v87, v78
	v_mov_b32_e32 v85, v78
	v_mov_b32_e32 v91, v78
	v_mov_b32_e32 v89, v78
	v_mov_b32_e32 v93, v78
	v_mov_b32_e32 v95, v78
	global_load_dwordx2 v[198:199], v[76:77], off
	global_load_dwordx2 v[200:201], v[74:75], off
	global_load_dwordx2 v[202:203], v[72:73], off
	global_load_dwordx2 v[204:205], v[70:71], off
	global_load_dwordx2 v[206:207], v[68:69], off
	global_load_dwordx2 v[208:209], v[66:67], off
	global_load_dwordx2 v[210:211], v[64:65], off
	global_load_dwordx2 v[212:213], v[62:63], off
	global_load_dwordx2 v[214:215], v[60:61], off
	global_load_dwordx2 v[216:217], v[58:59], off
	global_load_dwordx2 v[218:219], v[56:57], off
	global_load_dwordx2 v[220:221], v[54:55], off
	global_load_dwordx2 v[222:223], v[52:53], off
	global_load_dwordx2 v[224:225], v[6:7], off
	global_load_dwordx2 v[226:227], v[4:5], off
	global_load_dwordx2 v[228:229], v[2:3], off
	s_waitcnt lgkmcnt(0)
	s_barrier
.LBB0_114:
	s_add_u32 s98, s88, 0xc0000
	s_min_u32 s98, s98, 0x240000
	s_mov_b32 s99, 0
	v_lshl_add_u64 v[126:127], v[76:77], 0, s[88:89]
	ds_read_b128 v[122:125], v10
	ds_read_b128 v[132:135], v10 offset:16
	ds_read2_b32 v[136:137], v10 offset0:8 offset1:32
	v_add_u32_e32 v51, 0x200, v10
	s_waitcnt vmcnt(15) lgkmcnt(2)
	v_pk_fma_f32 v[138:139], v[198:199], v[122:123], v[78:79] op_sel_hi:[1, 0, 1]
	v_mov_b32_e32 v78, v125
	v_pk_fma_f32 v[86:87], v[198:199], v[78:79], v[86:87] op_sel_hi:[1, 0, 1]
	s_waitcnt lgkmcnt(1)
	v_mov_b32_e32 v78, v135
	v_pk_fma_f32 v[122:123], v[198:199], v[122:123], v[82:83] op_sel:[0, 1, 0]
	v_pk_fma_f32 v[140:141], v[198:199], v[124:125], v[80:81] op_sel_hi:[1, 0, 1]
	v_pk_fma_f32 v[124:125], v[198:199], v[132:133], v[84:85] op_sel_hi:[1, 0, 1]
	v_pk_fma_f32 v[90:91], v[198:199], v[132:133], v[90:91] op_sel:[0, 1, 0]
	v_pk_fma_f32 v[88:89], v[198:199], v[134:135], v[88:89] op_sel_hi:[1, 0, 1]
	v_pk_fma_f32 v[92:93], v[198:199], v[78:79], v[92:93] op_sel_hi:[1, 0, 1]
	s_waitcnt lgkmcnt(0)
	v_pk_fma_f32 v[94:95], v[198:199], v[136:137], v[94:95] op_sel_hi:[1, 0, 1]
	v_lshl_add_u64 v[230:231], v[76:77], 0, s[98:99]
	global_load_dwordx2 v[198:199], v[230:231], off
	v_lshl_add_u64 v[126:127], v[74:75], 0, s[88:89]
	ds_read_b128 v[78:81], v10 offset:96
	ds_read_b128 v[82:85], v10 offset:112
	s_waitcnt vmcnt(15) lgkmcnt(1)
	v_pk_fma_f32 v[132:133], v[200:201], v[78:79], v[138:139] op_sel_hi:[1, 0, 1]
	v_pk_fma_f32 v[122:123], v[200:201], v[78:79], v[122:123] op_sel:[0, 1, 0]
	v_mov_b32_e32 v78, v81
	v_pk_fma_f32 v[86:87], v[200:201], v[78:79], v[86:87] op_sel_hi:[1, 0, 1]
	s_waitcnt lgkmcnt(0)
	v_mov_b32_e32 v78, v85
	v_pk_fma_f32 v[92:93], v[200:201], v[78:79], v[92:93] op_sel_hi:[1, 0, 1]
	v_mov_b32_e32 v78, v137
	v_pk_fma_f32 v[134:135], v[200:201], v[80:81], v[140:141] op_sel_hi:[1, 0, 1]
	v_pk_fma_f32 v[124:125], v[200:201], v[82:83], v[124:125] op_sel_hi:[1, 0, 1]
	v_pk_fma_f32 v[90:91], v[200:201], v[82:83], v[90:91] op_sel:[0, 1, 0]
	v_pk_fma_f32 v[88:89], v[200:201], v[84:85], v[88:89] op_sel_hi:[1, 0, 1]
	v_pk_fma_f32 v[94:95], v[200:201], v[78:79], v[94:95] op_sel_hi:[1, 0, 1]
	v_lshl_add_u64 v[230:231], v[74:75], 0, s[98:99]
	global_load_dwordx2 v[200:201], v[230:231], off
	v_lshl_add_u64 v[126:127], v[72:73], 0, s[88:89]
	ds_read_b128 v[78:81], v10 offset:192
	ds_read_b128 v[82:85], v10 offset:208
	ds_read2_b32 v[136:137], v10 offset0:56 offset1:80
	s_waitcnt vmcnt(15) lgkmcnt(2)
	v_pk_fma_f32 v[132:133], v[202:203], v[78:79], v[132:133] op_sel_hi:[1, 0, 1]
	v_pk_fma_f32 v[122:123], v[202:203], v[78:79], v[122:123] op_sel:[0, 1, 0]
	v_mov_b32_e32 v78, v81
	v_pk_fma_f32 v[86:87], v[202:203], v[78:79], v[86:87] op_sel_hi:[1, 0, 1]
	s_waitcnt lgkmcnt(1)
	v_mov_b32_e32 v78, v85
	v_pk_fma_f32 v[134:135], v[202:203], v[80:81], v[134:135] op_sel_hi:[1, 0, 1]
	v_pk_fma_f32 v[124:125], v[202:203], v[82:83], v[124:125] op_sel_hi:[1, 0, 1]
	v_pk_fma_f32 v[90:91], v[202:203], v[82:83], v[90:91] op_sel:[0, 1, 0]
	v_pk_fma_f32 v[88:89], v[202:203], v[84:85], v[88:89] op_sel_hi:[1, 0, 1]
	v_pk_fma_f32 v[92:93], v[202:203], v[78:79], v[92:93] op_sel_hi:[1, 0, 1]
	s_waitcnt lgkmcnt(0)
	v_pk_fma_f32 v[94:95], v[202:203], v[136:137], v[94:95] op_sel_hi:[1, 0, 1]
	v_lshl_add_u64 v[230:231], v[72:73], 0, s[98:99]
	global_load_dwordx2 v[202:203], v[230:231], off
	v_lshl_add_u64 v[126:127], v[70:71], 0, s[88:89]
	ds_read_b128 v[78:81], v10 offset:288
	ds_read_b128 v[82:85], v10 offset:304
	s_waitcnt vmcnt(15) lgkmcnt(1)
	v_pk_fma_f32 v[132:133], v[204:205], v[78:79], v[132:133] op_sel_hi:[1, 0, 1]
	v_pk_fma_f32 v[122:123], v[204:205], v[78:79], v[122:123] op_sel:[0, 1, 0]
	v_mov_b32_e32 v78, v81
	v_pk_fma_f32 v[86:87], v[204:205], v[78:79], v[86:87] op_sel_hi:[1, 0, 1]
	s_waitcnt lgkmcnt(0)
	v_mov_b32_e32 v78, v85
	v_pk_fma_f32 v[92:93], v[204:205], v[78:79], v[92:93] op_sel_hi:[1, 0, 1]
	v_mov_b32_e32 v78, v137
	v_pk_fma_f32 v[134:135], v[204:205], v[80:81], v[134:135] op_sel_hi:[1, 0, 1]
	v_pk_fma_f32 v[124:125], v[204:205], v[82:83], v[124:125] op_sel_hi:[1, 0, 1]
	v_pk_fma_f32 v[90:91], v[204:205], v[82:83], v[90:91] op_sel:[0, 1, 0]
	v_pk_fma_f32 v[88:89], v[204:205], v[84:85], v[88:89] op_sel_hi:[1, 0, 1]
	v_pk_fma_f32 v[94:95], v[204:205], v[78:79], v[94:95] op_sel_hi:[1, 0, 1]
	v_lshl_add_u64 v[230:231], v[70:71], 0, s[98:99]
	global_load_dwordx2 v[204:205], v[230:231], off
	v_lshl_add_u64 v[126:127], v[68:69], 0, s[88:89]
	ds_read_b128 v[78:81], v10 offset:384
	ds_read_b128 v[82:85], v10 offset:400
	ds_read2_b32 v[136:137], v10 offset0:104 offset1:128
	s_waitcnt vmcnt(15) lgkmcnt(2)
	v_pk_fma_f32 v[132:133], v[206:207], v[78:79], v[132:133] op_sel_hi:[1, 0, 1]
	v_pk_fma_f32 v[122:123], v[206:207], v[78:79], v[122:123] op_sel:[0, 1, 0]
	v_mov_b32_e32 v78, v81
	v_pk_fma_f32 v[86:87], v[206:207], v[78:79], v[86:87] op_sel_hi:[1, 0, 1]
	s_waitcnt lgkmcnt(1)
	v_mov_b32_e32 v78, v85
	v_pk_fma_f32 v[134:135], v[206:207], v[80:81], v[134:135] op_sel_hi:[1, 0, 1]
	v_pk_fma_f32 v[124:125], v[206:207], v[82:83], v[124:125] op_sel_hi:[1, 0, 1]
	v_pk_fma_f32 v[90:91], v[206:207], v[82:83], v[90:91] op_sel:[0, 1, 0]
	v_pk_fma_f32 v[88:89], v[206:207], v[84:85], v[88:89] op_sel_hi:[1, 0, 1]
	v_pk_fma_f32 v[92:93], v[206:207], v[78:79], v[92:93] op_sel_hi:[1, 0, 1]
	s_waitcnt lgkmcnt(0)
	v_pk_fma_f32 v[94:95], v[206:207], v[136:137], v[94:95] op_sel_hi:[1, 0, 1]
	v_lshl_add_u64 v[230:231], v[68:69], 0, s[98:99]
	global_load_dwordx2 v[206:207], v[230:231], off
	v_lshl_add_u64 v[126:127], v[66:67], 0, s[88:89]
	ds_read_b128 v[78:81], v10 offset:480
	ds_read_b128 v[82:85], v10 offset:496
	s_waitcnt vmcnt(15) lgkmcnt(1)
	v_pk_fma_f32 v[132:133], v[208:209], v[78:79], v[132:133] op_sel_hi:[1, 0, 1]
	v_pk_fma_f32 v[122:123], v[208:209], v[78:79], v[122:123] op_sel:[0, 1, 0]
	v_mov_b32_e32 v78, v81
	v_pk_fma_f32 v[86:87], v[208:209], v[78:79], v[86:87] op_sel_hi:[1, 0, 1]
	s_waitcnt lgkmcnt(0)
	v_mov_b32_e32 v78, v85
	v_pk_fma_f32 v[92:93], v[208:209], v[78:79], v[92:93] op_sel_hi:[1, 0, 1]
	v_mov_b32_e32 v78, v137
	v_pk_fma_f32 v[134:135], v[208:209], v[80:81], v[134:135] op_sel_hi:[1, 0, 1]
	v_pk_fma_f32 v[124:125], v[208:209], v[82:83], v[124:125] op_sel_hi:[1, 0, 1]
	v_pk_fma_f32 v[90:91], v[208:209], v[82:83], v[90:91] op_sel:[0, 1, 0]
	v_pk_fma_f32 v[88:89], v[208:209], v[84:85], v[88:89] op_sel_hi:[1, 0, 1]
	v_pk_fma_f32 v[94:95], v[208:209], v[78:79], v[94:95] op_sel_hi:[1, 0, 1]
	v_lshl_add_u64 v[230:231], v[66:67], 0, s[98:99]
	global_load_dwordx2 v[208:209], v[230:231], off
	v_lshl_add_u64 v[126:127], v[64:65], 0, s[88:89]
	ds_read_b128 v[78:81], v10 offset:576
	ds_read_b128 v[82:85], v10 offset:592
	ds_read2_b32 v[136:137], v10 offset0:152 offset1:176
	s_waitcnt vmcnt(15) lgkmcnt(2)
	v_pk_fma_f32 v[132:133], v[210:211], v[78:79], v[132:133] op_sel_hi:[1, 0, 1]
	v_pk_fma_f32 v[122:123], v[210:211], v[78:79], v[122:123] op_sel:[0, 1, 0]
	v_mov_b32_e32 v78, v81
	v_pk_fma_f32 v[86:87], v[210:211], v[78:79], v[86:87] op_sel_hi:[1, 0, 1]
	s_waitcnt lgkmcnt(1)
	v_mov_b32_e32 v78, v85
	v_pk_fma_f32 v[134:135], v[210:211], v[80:81], v[134:135] op_sel_hi:[1, 0, 1]
	v_pk_fma_f32 v[124:125], v[210:211], v[82:83], v[124:125] op_sel_hi:[1, 0, 1]
	v_pk_fma_f32 v[90:91], v[210:211], v[82:83], v[90:91] op_sel:[0, 1, 0]
	v_pk_fma_f32 v[88:89], v[210:211], v[84:85], v[88:89] op_sel_hi:[1, 0, 1]
	v_pk_fma_f32 v[92:93], v[210:211], v[78:79], v[92:93] op_sel_hi:[1, 0, 1]
	s_waitcnt lgkmcnt(0)
	v_pk_fma_f32 v[94:95], v[210:211], v[136:137], v[94:95] op_sel_hi:[1, 0, 1]
	v_lshl_add_u64 v[230:231], v[64:65], 0, s[98:99]
	global_load_dwordx2 v[210:211], v[230:231], off
	v_lshl_add_u64 v[126:127], v[62:63], 0, s[88:89]
	ds_read_b128 v[78:81], v10 offset:672
	ds_read_b128 v[82:85], v10 offset:688
	s_waitcnt vmcnt(15) lgkmcnt(1)
	v_pk_fma_f32 v[132:133], v[212:213], v[78:79], v[132:133] op_sel_hi:[1, 0, 1]
	v_pk_fma_f32 v[122:123], v[212:213], v[78:79], v[122:123] op_sel:[0, 1, 0]
	v_mov_b32_e32 v78, v81
	v_pk_fma_f32 v[86:87], v[212:213], v[78:79], v[86:87] op_sel_hi:[1, 0, 1]
	s_waitcnt lgkmcnt(0)
	v_mov_b32_e32 v78, v85
	v_pk_fma_f32 v[92:93], v[212:213], v[78:79], v[92:93] op_sel_hi:[1, 0, 1]
	v_mov_b32_e32 v78, v137
	v_pk_fma_f32 v[134:135], v[212:213], v[80:81], v[134:135] op_sel_hi:[1, 0, 1]
	v_pk_fma_f32 v[124:125], v[212:213], v[82:83], v[124:125] op_sel_hi:[1, 0, 1]
	v_pk_fma_f32 v[90:91], v[212:213], v[82:83], v[90:91] op_sel:[0, 1, 0]
	v_pk_fma_f32 v[88:89], v[212:213], v[84:85], v[88:89] op_sel_hi:[1, 0, 1]
	v_pk_fma_f32 v[94:95], v[212:213], v[78:79], v[94:95] op_sel_hi:[1, 0, 1]
	v_lshl_add_u64 v[230:231], v[62:63], 0, s[98:99]
	global_load_dwordx2 v[212:213], v[230:231], off
	v_lshl_add_u64 v[126:127], v[60:61], 0, s[88:89]
	ds_read_b128 v[78:81], v10 offset:768
	ds_read_b128 v[82:85], v10 offset:784
	ds_read2_b32 v[136:137], v10 offset0:200 offset1:224
	s_waitcnt vmcnt(15) lgkmcnt(2)
	v_pk_fma_f32 v[132:133], v[214:215], v[78:79], v[132:133] op_sel_hi:[1, 0, 1]
	v_pk_fma_f32 v[122:123], v[214:215], v[78:79], v[122:123] op_sel:[0, 1, 0]
	v_mov_b32_e32 v78, v81
	v_pk_fma_f32 v[86:87], v[214:215], v[78:79], v[86:87] op_sel_hi:[1, 0, 1]
	s_waitcnt lgkmcnt(1)
	v_mov_b32_e32 v78, v85
	v_pk_fma_f32 v[134:135], v[214:215], v[80:81], v[134:135] op_sel_hi:[1, 0, 1]
	v_pk_fma_f32 v[124:125], v[214:215], v[82:83], v[124:125] op_sel_hi:[1, 0, 1]
	v_pk_fma_f32 v[90:91], v[214:215], v[82:83], v[90:91] op_sel:[0, 1, 0]
	v_pk_fma_f32 v[88:89], v[214:215], v[84:85], v[88:89] op_sel_hi:[1, 0, 1]
	v_pk_fma_f32 v[92:93], v[214:215], v[78:79], v[92:93] op_sel_hi:[1, 0, 1]
	s_waitcnt lgkmcnt(0)
	v_pk_fma_f32 v[94:95], v[214:215], v[136:137], v[94:95] op_sel_hi:[1, 0, 1]
	v_lshl_add_u64 v[230:231], v[60:61], 0, s[98:99]
	global_load_dwordx2 v[214:215], v[230:231], off
	v_lshl_add_u64 v[126:127], v[58:59], 0, s[88:89]
	ds_read_b128 v[78:81], v10 offset:864
	ds_read_b128 v[82:85], v10 offset:880
	s_waitcnt vmcnt(15) lgkmcnt(1)
	v_pk_fma_f32 v[132:133], v[216:217], v[78:79], v[132:133] op_sel_hi:[1, 0, 1]
	v_pk_fma_f32 v[122:123], v[216:217], v[78:79], v[122:123] op_sel:[0, 1, 0]
	v_mov_b32_e32 v78, v81
	v_pk_fma_f32 v[86:87], v[216:217], v[78:79], v[86:87] op_sel_hi:[1, 0, 1]
	s_waitcnt lgkmcnt(0)
	v_mov_b32_e32 v78, v85
	v_pk_fma_f32 v[92:93], v[216:217], v[78:79], v[92:93] op_sel_hi:[1, 0, 1]
	v_mov_b32_e32 v78, v137
	v_pk_fma_f32 v[134:135], v[216:217], v[80:81], v[134:135] op_sel_hi:[1, 0, 1]
	v_pk_fma_f32 v[124:125], v[216:217], v[82:83], v[124:125] op_sel_hi:[1, 0, 1]
	v_pk_fma_f32 v[90:91], v[216:217], v[82:83], v[90:91] op_sel:[0, 1, 0]
	v_pk_fma_f32 v[88:89], v[216:217], v[84:85], v[88:89] op_sel_hi:[1, 0, 1]
	v_pk_fma_f32 v[94:95], v[216:217], v[78:79], v[94:95] op_sel_hi:[1, 0, 1]
	v_lshl_add_u64 v[230:231], v[58:59], 0, s[98:99]
	global_load_dwordx2 v[216:217], v[230:231], off
	v_lshl_add_u64 v[126:127], v[56:57], 0, s[88:89]
	ds_read_b128 v[78:81], v10 offset:960
	ds_read_b128 v[82:85], v10 offset:976
	ds_read2_b32 v[136:137], v51 offset0:120 offset1:144
	v_add_u32_e32 v51, 0x400, v10
	s_waitcnt vmcnt(15) lgkmcnt(2)
	v_pk_fma_f32 v[132:133], v[218:219], v[78:79], v[132:133] op_sel_hi:[1, 0, 1]
	v_pk_fma_f32 v[122:123], v[218:219], v[78:79], v[122:123] op_sel:[0, 1, 0]
	v_mov_b32_e32 v78, v81
	v_pk_fma_f32 v[86:87], v[218:219], v[78:79], v[86:87] op_sel_hi:[1, 0, 1]
	s_waitcnt lgkmcnt(1)
	v_mov_b32_e32 v78, v85
	v_pk_fma_f32 v[134:135], v[218:219], v[80:81], v[134:135] op_sel_hi:[1, 0, 1]
	v_pk_fma_f32 v[124:125], v[218:219], v[82:83], v[124:125] op_sel_hi:[1, 0, 1]
	v_pk_fma_f32 v[90:91], v[218:219], v[82:83], v[90:91] op_sel:[0, 1, 0]
	v_pk_fma_f32 v[88:89], v[218:219], v[84:85], v[88:89] op_sel_hi:[1, 0, 1]
	v_pk_fma_f32 v[92:93], v[218:219], v[78:79], v[92:93] op_sel_hi:[1, 0, 1]
	s_waitcnt lgkmcnt(0)
	v_pk_fma_f32 v[94:95], v[218:219], v[136:137], v[94:95] op_sel_hi:[1, 0, 1]
	v_lshl_add_u64 v[230:231], v[56:57], 0, s[98:99]
	global_load_dwordx2 v[218:219], v[230:231], off
	v_lshl_add_u64 v[126:127], v[54:55], 0, s[88:89]
	ds_read_b128 v[78:81], v10 offset:1056
	ds_read_b128 v[82:85], v10 offset:1072
	s_waitcnt vmcnt(15) lgkmcnt(1)
	v_pk_fma_f32 v[132:133], v[220:221], v[78:79], v[132:133] op_sel_hi:[1, 0, 1]
	v_pk_fma_f32 v[122:123], v[220:221], v[78:79], v[122:123] op_sel:[0, 1, 0]
	v_mov_b32_e32 v78, v81
	v_pk_fma_f32 v[86:87], v[220:221], v[78:79], v[86:87] op_sel_hi:[1, 0, 1]
	s_waitcnt lgkmcnt(0)
	v_mov_b32_e32 v78, v85
	v_pk_fma_f32 v[92:93], v[220:221], v[78:79], v[92:93] op_sel_hi:[1, 0, 1]
	v_mov_b32_e32 v78, v137
	v_pk_fma_f32 v[134:135], v[220:221], v[80:81], v[134:135] op_sel_hi:[1, 0, 1]
	v_pk_fma_f32 v[124:125], v[220:221], v[82:83], v[124:125] op_sel_hi:[1, 0, 1]
	v_pk_fma_f32 v[90:91], v[220:221], v[82:83], v[90:91] op_sel:[0, 1, 0]
	v_pk_fma_f32 v[88:89], v[220:221], v[84:85], v[88:89] op_sel_hi:[1, 0, 1]
	v_pk_fma_f32 v[94:95], v[220:221], v[78:79], v[94:95] op_sel_hi:[1, 0, 1]
	v_lshl_add_u64 v[230:231], v[54:55], 0, s[98:99]
	global_load_dwordx2 v[220:221], v[230:231], off
	v_lshl_add_u64 v[126:127], v[52:53], 0, s[88:89]
	ds_read_b128 v[78:81], v10 offset:1152
	ds_read_b128 v[82:85], v10 offset:1168
	ds_read2_b32 v[136:137], v51 offset0:40 offset1:64
	s_waitcnt vmcnt(15) lgkmcnt(2)
	v_pk_fma_f32 v[132:133], v[222:223], v[78:79], v[132:133] op_sel_hi:[1, 0, 1]
	v_pk_fma_f32 v[122:123], v[222:223], v[78:79], v[122:123] op_sel:[0, 1, 0]
	v_mov_b32_e32 v78, v81
	v_pk_fma_f32 v[86:87], v[222:223], v[78:79], v[86:87] op_sel_hi:[1, 0, 1]
	s_waitcnt lgkmcnt(1)
	v_mov_b32_e32 v78, v85
	v_pk_fma_f32 v[134:135], v[222:223], v[80:81], v[134:135] op_sel_hi:[1, 0, 1]
	v_pk_fma_f32 v[124:125], v[222:223], v[82:83], v[124:125] op_sel_hi:[1, 0, 1]
	v_pk_fma_f32 v[90:91], v[222:223], v[82:83], v[90:91] op_sel:[0, 1, 0]
	v_pk_fma_f32 v[88:89], v[222:223], v[84:85], v[88:89] op_sel_hi:[1, 0, 1]
	v_pk_fma_f32 v[92:93], v[222:223], v[78:79], v[92:93] op_sel_hi:[1, 0, 1]
	s_waitcnt lgkmcnt(0)
	v_pk_fma_f32 v[94:95], v[222:223], v[136:137], v[94:95] op_sel_hi:[1, 0, 1]
	v_lshl_add_u64 v[230:231], v[52:53], 0, s[98:99]
	global_load_dwordx2 v[222:223], v[230:231], off
	v_lshl_add_u64 v[126:127], v[6:7], 0, s[88:89]
	ds_read_b128 v[78:81], v10 offset:1248
	ds_read_b128 v[82:85], v10 offset:1264
	s_waitcnt vmcnt(15) lgkmcnt(1)
	v_pk_fma_f32 v[132:133], v[224:225], v[78:79], v[132:133] op_sel_hi:[1, 0, 1]
	v_pk_fma_f32 v[122:123], v[224:225], v[78:79], v[122:123] op_sel:[0, 1, 0]
	v_mov_b32_e32 v78, v81
	v_pk_fma_f32 v[86:87], v[224:225], v[78:79], v[86:87] op_sel_hi:[1, 0, 1]
	s_waitcnt lgkmcnt(0)
	v_mov_b32_e32 v78, v85
	v_pk_fma_f32 v[92:93], v[224:225], v[78:79], v[92:93] op_sel_hi:[1, 0, 1]
	v_mov_b32_e32 v78, v137
	v_pk_fma_f32 v[134:135], v[224:225], v[80:81], v[134:135] op_sel_hi:[1, 0, 1]
	v_pk_fma_f32 v[124:125], v[224:225], v[82:83], v[124:125] op_sel_hi:[1, 0, 1]
	v_pk_fma_f32 v[90:91], v[224:225], v[82:83], v[90:91] op_sel:[0, 1, 0]
	v_pk_fma_f32 v[88:89], v[224:225], v[84:85], v[88:89] op_sel_hi:[1, 0, 1]
	v_pk_fma_f32 v[94:95], v[224:225], v[78:79], v[94:95] op_sel_hi:[1, 0, 1]
	v_lshl_add_u64 v[230:231], v[6:7], 0, s[98:99]
	global_load_dwordx2 v[224:225], v[230:231], off
	v_lshl_add_u64 v[126:127], v[4:5], 0, s[88:89]
	ds_read_b128 v[78:81], v10 offset:1344
	ds_read_b128 v[82:85], v10 offset:1360
	ds_read2_b32 v[136:137], v51 offset0:88 offset1:112
	s_waitcnt vmcnt(15) lgkmcnt(2)
	v_pk_fma_f32 v[132:133], v[226:227], v[78:79], v[132:133] op_sel_hi:[1, 0, 1]
	v_pk_fma_f32 v[122:123], v[226:227], v[78:79], v[122:123] op_sel:[0, 1, 0]
	v_mov_b32_e32 v78, v81
	v_pk_fma_f32 v[86:87], v[226:227], v[78:79], v[86:87] op_sel_hi:[1, 0, 1]
	s_waitcnt lgkmcnt(1)
	v_mov_b32_e32 v78, v85
	v_pk_fma_f32 v[140:141], v[226:227], v[78:79], v[92:93] op_sel_hi:[1, 0, 1]
	v_lshl_add_u64 v[78:79], v[2:3], 0, s[88:89]
	v_pk_fma_f32 v[134:135], v[226:227], v[80:81], v[134:135] op_sel_hi:[1, 0, 1]
	v_pk_fma_f32 v[124:125], v[226:227], v[82:83], v[124:125] op_sel_hi:[1, 0, 1]
	v_pk_fma_f32 v[138:139], v[226:227], v[82:83], v[90:91] op_sel:[0, 1, 0]
	v_pk_fma_f32 v[88:89], v[226:227], v[84:85], v[88:89] op_sel_hi:[1, 0, 1]
	s_waitcnt lgkmcnt(0)
	v_pk_fma_f32 v[94:95], v[226:227], v[136:137], v[94:95] op_sel_hi:[1, 0, 1]
	v_lshl_add_u64 v[230:231], v[4:5], 0, s[98:99]
	global_load_dwordx2 v[226:227], v[230:231], off
	ds_read_b128 v[82:85], v10 offset:1440
	ds_read_b128 v[90:93], v10 offset:1456
	s_add_u32 s88, s88, 0xc0000
	s_addc_u32 s89, s89, 0
	v_add_u32_e32 v10, 0x600, v10
	s_cmp_eq_u32 s88, 0x300000
	s_waitcnt vmcnt(15) lgkmcnt(1)
	v_pk_fma_f32 v[78:79], v[228:229], v[82:83], v[132:133] op_sel_hi:[1, 0, 1]
	v_pk_fma_f32 v[82:83], v[228:229], v[82:83], v[122:123] op_sel:[0, 1, 0]
	v_pk_fma_f32 v[80:81], v[228:229], v[84:85], v[134:135] op_sel_hi:[1, 0, 1]
	v_mov_b32_e32 v84, v85
	s_waitcnt lgkmcnt(0)
	v_pk_fma_f32 v[88:89], v[228:229], v[92:93], v[88:89] op_sel_hi:[1, 0, 1]
	v_mov_b32_e32 v92, v93
	v_mov_b32_e32 v122, v137
	v_pk_fma_f32 v[86:87], v[228:229], v[84:85], v[86:87] op_sel_hi:[1, 0, 1]
	v_pk_fma_f32 v[84:85], v[228:229], v[90:91], v[124:125] op_sel_hi:[1, 0, 1]
	v_pk_fma_f32 v[90:91], v[228:229], v[90:91], v[138:139] op_sel:[0, 1, 0]
	v_pk_fma_f32 v[92:93], v[228:229], v[92:93], v[140:141] op_sel_hi:[1, 0, 1]
	v_pk_fma_f32 v[94:95], v[228:229], v[122:123], v[94:95] op_sel_hi:[1, 0, 1]
	v_lshl_add_u64 v[230:231], v[2:3], 0, s[98:99]
	global_load_dwordx2 v[228:229], v[230:231], off
	s_cbranch_scc0 .LBB0_114
	v_add_u32_e32 v2, 0xc000, v116
	ds_write2_b64 v2, v[78:79], v[82:83] offset1:32
	ds_write2_b64 v2, v[80:81], v[86:87] offset0:64 offset1:96
	ds_write2_b64 v2, v[84:85], v[90:91] offset0:128 offset1:160
	ds_write2_b64 v2, v[88:89], v[92:93] offset0:192 offset1:224
	ds_write_b64 v116, v[94:95] offset:51200
	s_waitcnt lgkmcnt(0)
	s_barrier
	s_and_saveexec_b64 s[16:17], s[6:7]
	s_cbranch_execz .LBB0_23
	s_mul_i32 s19, s20, 0x1800
	s_add_i32 s19, s19, s18
	v_or_b32_e32 v2, s19, v131
	v_mad_u64_u32 v[4:5], s[18:19], s20, 9, v[130:131]
	v_mov_b64_e32 v[6:7], s[14:15]
	s_movk_i32 s14, 0x6000
	v_ashrrev_i32_e32 v3, 31, v2
	v_mad_i64_i32 v[4:5], s[14:15], v4, s14, v[6:7]
	v_lshl_add_u64 v[2:3], v[2:3], 2, s[62:63]
	v_lshl_add_u64 v[4:5], v[48:49], 0, v[4:5]
	s_mov_b64 s[14:15], 0
	v_mov_b32_e32 v6, v112
	v_mov_b32_e32 v7, v111

.LBB0_1334:
	s_or_b64 exec, exec, s[0:1]
	s_add_i32 s0, s24, 0x60
	s_mul_hi_i32 s1, s0, 0x2aaaaaab
	s_lshr_b32 s14, s1, 31
	s_ashr_i32 s20, s1, 4
	s_add_i32 s20, s20, s14
	s_mul_i32 s1, s20, 0x60
	s_sub_i32 s0, s0, s1
	s_lshl_b32 s14, s0, 6
	s_ashr_i32 s15, s14, 31
	s_mul_i32 s16, s20, 0x1800000
	s_lshl_b64 s[0:1], s[14:15], 2
	s_mul_hi_i32 s17, s20, 0x1800000
	s_add_u32 s16, s16, s0
	s_addc_u32 s17, s17, s1
	v_mov_b32_e32 v70, 0
	v_lshl_add_u64 v[38:39], v[4:5], 0, s[16:17]
	v_lshl_add_u64 v[40:41], v[6:7], 0, s[16:17]
	v_lshl_add_u64 v[42:43], v[8:9], 0, s[16:17]
	v_lshl_add_u64 v[44:45], v[10:11], 0, s[16:17]
	v_lshl_add_u64 v[46:47], v[12:13], 0, s[16:17]
	v_lshl_add_u64 v[48:49], v[14:15], 0, s[16:17]
	v_lshl_add_u64 v[50:51], v[16:17], 0, s[16:17]
	v_lshl_add_u64 v[52:53], v[18:19], 0, s[16:17]
	v_lshl_add_u64 v[54:55], v[20:21], 0, s[16:17]
	v_lshl_add_u64 v[56:57], v[22:23], 0, s[16:17]
	v_lshl_add_u64 v[58:59], v[24:25], 0, s[16:17]
	v_lshl_add_u64 v[60:61], v[26:27], 0, s[16:17]
	v_lshl_add_u64 v[62:63], v[28:29], 0, s[16:17]
	v_lshl_add_u64 v[64:65], v[30:31], 0, s[16:17]
	v_lshl_add_u64 v[66:67], v[32:33], 0, s[16:17]
	v_lshl_add_u64 v[68:69], v[34:35], 0, s[16:17]
	s_mov_b64 s[18:19], 0
	v_mov_b32_e32 v0, v90
	v_mov_b32_e32 v74, 0
	v_mov_b32_e32 v72, 0
	v_mov_b32_e32 v78, 0
	v_mov_b32_e32 v76, 0
	v_mov_b32_e32 v82, 0
	v_mov_b32_e32 v80, 0
	v_mov_b32_e32 v84, 0
	v_mov_b32_e32 v86, 0
	v_mov_b32_e32 v71, v70
	v_mov_b32_e32 v75, v70
	v_mov_b32_e32 v73, v70
	v_mov_b32_e32 v79, v70
	v_mov_b32_e32 v77, v70
	v_mov_b32_e32 v83, v70
	v_mov_b32_e32 v81, v70
	v_mov_b32_e32 v85, v70
	v_mov_b32_e32 v87, v70
	global_load_dwordx2 v[198:199], v[68:69], off
	global_load_dwordx2 v[200:201], v[66:67], off
	global_load_dwordx2 v[202:203], v[64:65], off
	global_load_dwordx2 v[204:205], v[62:63], off
	global_load_dwordx2 v[206:207], v[60:61], off
	global_load_dwordx2 v[208:209], v[58:59], off
	global_load_dwordx2 v[210:211], v[56:57], off
	global_load_dwordx2 v[212:213], v[54:55], off
	global_load_dwordx2 v[214:215], v[52:53], off
	global_load_dwordx2 v[216:217], v[50:51], off
	global_load_dwordx2 v[218:219], v[48:49], off
	global_load_dwordx2 v[220:221], v[46:47], off
	global_load_dwordx2 v[222:223], v[44:45], off
	global_load_dwordx2 v[224:225], v[42:43], off
	global_load_dwordx2 v[226:227], v[40:41], off
	global_load_dwordx2 v[228:229], v[38:39], off
	s_waitcnt lgkmcnt(0)
	s_barrier
.LBB0_1335:
	s_add_u32 s98, s18, 0xc0000
	s_min_u32 s98, s98, 0x240000
	s_mov_b32 s99, 0
	v_lshl_add_u64 v[104:105], v[68:69], 0, s[18:19]
	ds_read_b128 v[96:99], v0
	ds_read_b128 v[100:103], v0 offset:16
	ds_read2_b32 v[106:107], v0 offset0:8 offset1:32
	v_add_u32_e32 v95, 0x200, v0
	s_waitcnt vmcnt(15) lgkmcnt(2)
	v_pk_fma_f32 v[108:109], v[198:199], v[96:97], v[70:71] op_sel_hi:[1, 0, 1]
	v_mov_b32_e32 v70, v99
	v_pk_fma_f32 v[110:111], v[198:199], v[98:99], v[72:73] op_sel_hi:[1, 0, 1]
	v_pk_fma_f32 v[78:79], v[198:199], v[70:71], v[78:79] op_sel_hi:[1, 0, 1]
	s_waitcnt lgkmcnt(1)
	v_pk_fma_f32 v[98:99], v[198:199], v[100:101], v[76:77] op_sel_hi:[1, 0, 1]
	v_pk_fma_f32 v[82:83], v[198:199], v[100:101], v[82:83] op_sel:[0, 1, 0]
	v_mov_b32_e32 v70, v103
	v_lshl_add_u64 v[100:101], v[66:67], 0, s[18:19]
	v_pk_fma_f32 v[96:97], v[198:199], v[96:97], v[74:75] op_sel:[0, 1, 0]
	v_pk_fma_f32 v[84:85], v[198:199], v[70:71], v[84:85] op_sel_hi:[1, 0, 1]
	ds_read_b128 v[70:73], v0 offset:96
	ds_read_b128 v[74:77], v0 offset:112
	v_pk_fma_f32 v[80:81], v[198:199], v[102:103], v[80:81] op_sel_hi:[1, 0, 1]
	s_waitcnt lgkmcnt(2)
	v_pk_fma_f32 v[86:87], v[198:199], v[106:107], v[86:87] op_sel_hi:[1, 0, 1]
	v_lshl_add_u64 v[230:231], v[68:69], 0, s[98:99]
	global_load_dwordx2 v[198:199], v[230:231], off
	s_waitcnt vmcnt(15) lgkmcnt(1)
	v_pk_fma_f32 v[102:103], v[200:201], v[70:71], v[108:109] op_sel_hi:[1, 0, 1]
	v_pk_fma_f32 v[96:97], v[200:201], v[70:71], v[96:97] op_sel:[0, 1, 0]
	v_mov_b32_e32 v70, v73
	v_pk_fma_f32 v[78:79], v[200:201], v[70:71], v[78:79] op_sel_hi:[1, 0, 1]
	s_waitcnt lgkmcnt(0)
	v_mov_b32_e32 v70, v77
	v_pk_fma_f32 v[84:85], v[200:201], v[70:71], v[84:85] op_sel_hi:[1, 0, 1]
	v_mov_b32_e32 v70, v107
	v_pk_fma_f32 v[104:105], v[200:201], v[72:73], v[110:111] op_sel_hi:[1, 0, 1]
	v_pk_fma_f32 v[98:99], v[200:201], v[74:75], v[98:99] op_sel_hi:[1, 0, 1]
	v_pk_fma_f32 v[82:83], v[200:201], v[74:75], v[82:83] op_sel:[0, 1, 0]
	v_pk_fma_f32 v[80:81], v[200:201], v[76:77], v[80:81] op_sel_hi:[1, 0, 1]
	v_pk_fma_f32 v[86:87], v[200:201], v[70:71], v[86:87] op_sel_hi:[1, 0, 1]
	v_lshl_add_u64 v[230:231], v[66:67], 0, s[98:99]
	global_load_dwordx2 v[200:201], v[230:231], off
	v_lshl_add_u64 v[100:101], v[64:65], 0, s[18:19]
	ds_read_b128 v[70:73], v0 offset:192
	ds_read_b128 v[74:77], v0 offset:208
	ds_read2_b32 v[106:107], v0 offset0:56 offset1:80
	s_waitcnt vmcnt(15) lgkmcnt(2)
	v_pk_fma_f32 v[102:103], v[202:203], v[70:71], v[102:103] op_sel_hi:[1, 0, 1]
	v_pk_fma_f32 v[96:97], v[202:203], v[70:71], v[96:97] op_sel:[0, 1, 0]
	v_mov_b32_e32 v70, v73
	v_pk_fma_f32 v[78:79], v[202:203], v[70:71], v[78:79] op_sel_hi:[1, 0, 1]
	s_waitcnt lgkmcnt(1)
	v_mov_b32_e32 v70, v77
	v_pk_fma_f32 v[104:105], v[202:203], v[72:73], v[104:105] op_sel_hi:[1, 0, 1]
	v_pk_fma_f32 v[98:99], v[202:203], v[74:75], v[98:99] op_sel_hi:[1, 0, 1]
	v_pk_fma_f32 v[82:83], v[202:203], v[74:75], v[82:83] op_sel:[0, 1, 0]
	v_pk_fma_f32 v[80:81], v[202:203], v[76:77], v[80:81] op_sel_hi:[1, 0, 1]
	v_pk_fma_f32 v[84:85], v[202:203], v[70:71], v[84:85] op_sel_hi:[1, 0, 1]
	s_waitcnt lgkmcnt(0)
	v_pk_fma_f32 v[86:87], v[202:203], v[106:107], v[86:87] op_sel_hi:[1, 0, 1]
	v_lshl_add_u64 v[230:231], v[64:65], 0, s[98:99]
	global_load_dwordx2 v[202:203], v[230:231], off
	v_lshl_add_u64 v[100:101], v[62:63], 0, s[18:19]
	ds_read_b128 v[70:73], v0 offset:288
	ds_read_b128 v[74:77], v0 offset:304
	s_waitcnt vmcnt(15) lgkmcnt(1)
	v_pk_fma_f32 v[102:103], v[204:205], v[70:71], v[102:103] op_sel_hi:[1, 0, 1]
	v_pk_fma_f32 v[96:97], v[204:205], v[70:71], v[96:97] op_sel:[0, 1, 0]
	v_mov_b32_e32 v70, v73
	v_pk_fma_f32 v[78:79], v[204:205], v[70:71], v[78:79] op_sel_hi:[1, 0, 1]
	s_waitcnt lgkmcnt(0)
	v_mov_b32_e32 v70, v77
	v_pk_fma_f32 v[84:85], v[204:205], v[70:71], v[84:85] op_sel_hi:[1, 0, 1]
	v_mov_b32_e32 v70, v107
	v_pk_fma_f32 v[104:105], v[204:205], v[72:73], v[104:105] op_sel_hi:[1, 0, 1]
	v_pk_fma_f32 v[98:99], v[204:205], v[74:75], v[98:99] op_sel_hi:[1, 0, 1]
	v_pk_fma_f32 v[82:83], v[204:205], v[74:75], v[82:83] op_sel:[0, 1, 0]
	v_pk_fma_f32 v[80:81], v[204:205], v[76:77], v[80:81] op_sel_hi:[1, 0, 1]
	v_pk_fma_f32 v[86:87], v[204:205], v[70:71], v[86:87] op_sel_hi:[1, 0, 1]
	v_lshl_add_u64 v[230:231], v[62:63], 0, s[98:99]
	global_load_dwordx2 v[204:205], v[230:231], off
	v_lshl_add_u64 v[100:101], v[60:61], 0, s[18:19]
	ds_read_b128 v[70:73], v0 offset:384
	ds_read_b128 v[74:77], v0 offset:400
	ds_read2_b32 v[106:107], v0 offset0:104 offset1:128
	s_waitcnt vmcnt(15) lgkmcnt(2)
	v_pk_fma_f32 v[102:103], v[206:207], v[70:71], v[102:103] op_sel_hi:[1, 0, 1]
	v_pk_fma_f32 v[96:97], v[206:207], v[70:71], v[96:97] op_sel:[0, 1, 0]
	v_mov_b32_e32 v70, v73
	v_pk_fma_f32 v[78:79], v[206:207], v[70:71], v[78:79] op_sel_hi:[1, 0, 1]
	s_waitcnt lgkmcnt(1)
	v_mov_b32_e32 v70, v77
	v_pk_fma_f32 v[104:105], v[206:207], v[72:73], v[104:105] op_sel_hi:[1, 0, 1]
	v_pk_fma_f32 v[98:99], v[206:207], v[74:75], v[98:99] op_sel_hi:[1, 0, 1]
	v_pk_fma_f32 v[82:83], v[206:207], v[74:75], v[82:83] op_sel:[0, 1, 0]
	v_pk_fma_f32 v[80:81], v[206:207], v[76:77], v[80:81] op_sel_hi:[1, 0, 1]
	v_pk_fma_f32 v[84:85], v[206:207], v[70:71], v[84:85] op_sel_hi:[1, 0, 1]
	s_waitcnt lgkmcnt(0)
	v_pk_fma_f32 v[86:87], v[206:207], v[106:107], v[86:87] op_sel_hi:[1, 0, 1]
	v_lshl_add_u64 v[230:231], v[60:61], 0, s[98:99]
	global_load_dwordx2 v[206:207], v[230:231], off
	v_lshl_add_u64 v[100:101], v[58:59], 0, s[18:19]
	ds_read_b128 v[70:73], v0 offset:480
	ds_read_b128 v[74:77], v0 offset:496
	s_waitcnt vmcnt(15) lgkmcnt(1)
	v_pk_fma_f32 v[102:103], v[208:209], v[70:71], v[102:103] op_sel_hi:[1, 0, 1]
	v_pk_fma_f32 v[96:97], v[208:209], v[70:71], v[96:97] op_sel:[0, 1, 0]
	v_mov_b32_e32 v70, v73
	v_pk_fma_f32 v[78:79], v[208:209], v[70:71], v[78:79] op_sel_hi:[1, 0, 1]
	s_waitcnt lgkmcnt(0)
	v_mov_b32_e32 v70, v77
	v_pk_fma_f32 v[84:85], v[208:209], v[70:71], v[84:85] op_sel_hi:[1, 0, 1]
	v_mov_b32_e32 v70, v107
	v_pk_fma_f32 v[104:105], v[208:209], v[72:73], v[104:105] op_sel_hi:[1, 0, 1]
	v_pk_fma_f32 v[98:99], v[208:209], v[74:75], v[98:99] op_sel_hi:[1, 0, 1]
	v_pk_fma_f32 v[82:83], v[208:209], v[74:75], v[82:83] op_sel:[0, 1, 0]
	v_pk_fma_f32 v[80:81], v[208:209], v[76:77], v[80:81] op_sel_hi:[1, 0, 1]
	v_pk_fma_f32 v[86:87], v[208:209], v[70:71], v[86:87] op_sel_hi:[1, 0, 1]
	v_lshl_add_u64 v[230:231], v[58:59], 0, s[98:99]
	global_load_dwordx2 v[208:209], v[230:231], off
	v_lshl_add_u64 v[100:101], v[56:57], 0, s[18:19]
	ds_read_b128 v[70:73], v0 offset:576
	ds_read_b128 v[74:77], v0 offset:592
	ds_read2_b32 v[106:107], v0 offset0:152 offset1:176
	s_waitcnt vmcnt(15) lgkmcnt(2)
	v_pk_fma_f32 v[102:103], v[210:211], v[70:71], v[102:103] op_sel_hi:[1, 0, 1]
	v_pk_fma_f32 v[96:97], v[210:211], v[70:71], v[96:97] op_sel:[0, 1, 0]
	v_mov_b32_e32 v70, v73
	v_pk_fma_f32 v[78:79], v[210:211], v[70:71], v[78:79] op_sel_hi:[1, 0, 1]
	s_waitcnt lgkmcnt(1)
	v_mov_b32_e32 v70, v77
	v_pk_fma_f32 v[104:105], v[210:211], v[72:73], v[104:105] op_sel_hi:[1, 0, 1]
	v_pk_fma_f32 v[98:99], v[210:211], v[74:75], v[98:99] op_sel_hi:[1, 0, 1]
	v_pk_fma_f32 v[82:83], v[210:211], v[74:75], v[82:83] op_sel:[0, 1, 0]
	v_pk_fma_f32 v[80:81], v[210:211], v[76:77], v[80:81] op_sel_hi:[1, 0, 1]
	v_pk_fma_f32 v[84:85], v[210:211], v[70:71], v[84:85] op_sel_hi:[1, 0, 1]
	s_waitcnt lgkmcnt(0)
	v_pk_fma_f32 v[86:87], v[210:211], v[106:107], v[86:87] op_sel_hi:[1, 0, 1]
	v_lshl_add_u64 v[230:231], v[56:57], 0, s[98:99]
	global_load_dwordx2 v[210:211], v[230:231], off
	v_lshl_add_u64 v[100:101], v[54:55], 0, s[18:19]
	ds_read_b128 v[70:73], v0 offset:672
	ds_read_b128 v[74:77], v0 offset:688
	s_waitcnt vmcnt(15) lgkmcnt(1)
	v_pk_fma_f32 v[102:103], v[212:213], v[70:71], v[102:103] op_sel_hi:[1, 0, 1]
	v_pk_fma_f32 v[96:97], v[212:213], v[70:71], v[96:97] op_sel:[0, 1, 0]
	v_mov_b32_e32 v70, v73
	v_pk_fma_f32 v[78:79], v[212:213], v[70:71], v[78:79] op_sel_hi:[1, 0, 1]
	s_waitcnt lgkmcnt(0)
	v_mov_b32_e32 v70, v77
	v_pk_fma_f32 v[84:85], v[212:213], v[70:71], v[84:85] op_sel_hi:[1, 0, 1]
	v_mov_b32_e32 v70, v107
	v_pk_fma_f32 v[104:105], v[212:213], v[72:73], v[104:105] op_sel_hi:[1, 0, 1]
	v_pk_fma_f32 v[98:99], v[212:213], v[74:75], v[98:99] op_sel_hi:[1, 0, 1]
	v_pk_fma_f32 v[82:83], v[212:213], v[74:75], v[82:83] op_sel:[0, 1, 0]
	v_pk_fma_f32 v[80:81], v[212:213], v[76:77], v[80:81] op_sel_hi:[1, 0, 1]
	v_pk_fma_f32 v[86:87], v[212:213], v[70:71], v[86:87] op_sel_hi:[1, 0, 1]
	v_lshl_add_u64 v[230:231], v[54:55], 0, s[98:99]
	global_load_dwordx2 v[212:213], v[230:231], off
	v_lshl_add_u64 v[100:101], v[52:53], 0, s[18:19]
	ds_read_b128 v[70:73], v0 offset:768
	ds_read_b128 v[74:77], v0 offset:784
	ds_read2_b32 v[106:107], v0 offset0:200 offset1:224
	s_waitcnt vmcnt(15) lgkmcnt(2)
	v_pk_fma_f32 v[102:103], v[214:215], v[70:71], v[102:103] op_sel_hi:[1, 0, 1]
	v_pk_fma_f32 v[96:97], v[214:215], v[70:71], v[96:97] op_sel:[0, 1, 0]
	v_mov_b32_e32 v70, v73
	v_pk_fma_f32 v[78:79], v[214:215], v[70:71], v[78:79] op_sel_hi:[1, 0, 1]
	s_waitcnt lgkmcnt(1)
	v_mov_b32_e32 v70, v77
	v_pk_fma_f32 v[104:105], v[214:215], v[72:73], v[104:105] op_sel_hi:[1, 0, 1]
	v_pk_fma_f32 v[98:99], v[214:215], v[74:75], v[98:99] op_sel_hi:[1, 0, 1]
	v_pk_fma_f32 v[82:83], v[214:215], v[74:75], v[82:83] op_sel:[0, 1, 0]
	v_pk_fma_f32 v[80:81], v[214:215], v[76:77], v[80:81] op_sel_hi:[1, 0, 1]
	v_pk_fma_f32 v[84:85], v[214:215], v[70:71], v[84:85] op_sel_hi:[1, 0, 1]
	s_waitcnt lgkmcnt(0)
	v_pk_fma_f32 v[86:87], v[214:215], v[106:107], v[86:87] op_sel_hi:[1, 0, 1]
	v_lshl_add_u64 v[230:231], v[52:53], 0, s[98:99]
	global_load_dwordx2 v[214:215], v[230:231], off
	v_lshl_add_u64 v[100:101], v[50:51], 0, s[18:19]
	ds_read_b128 v[70:73], v0 offset:864
	ds_read_b128 v[74:77], v0 offset:880
	s_waitcnt vmcnt(15) lgkmcnt(1)
	v_pk_fma_f32 v[102:103], v[216:217], v[70:71], v[102:103] op_sel_hi:[1, 0, 1]
	v_pk_fma_f32 v[96:97], v[216:217], v[70:71], v[96:97] op_sel:[0, 1, 0]
	v_mov_b32_e32 v70, v73
	v_pk_fma_f32 v[78:79], v[216:217], v[70:71], v[78:79] op_sel_hi:[1, 0, 1]
	s_waitcnt lgkmcnt(0)
	v_mov_b32_e32 v70, v77
	v_pk_fma_f32 v[84:85], v[216:217], v[70:71], v[84:85] op_sel_hi:[1, 0, 1]
	v_mov_b32_e32 v70, v107
	v_pk_fma_f32 v[104:105], v[216:217], v[72:73], v[104:105] op_sel_hi:[1, 0, 1]
	v_pk_fma_f32 v[98:99], v[216:217], v[74:75], v[98:99] op_sel_hi:[1, 0, 1]
	v_pk_fma_f32 v[82:83], v[216:217], v[74:75], v[82:83] op_sel:[0, 1, 0]
	v_pk_fma_f32 v[80:81], v[216:217], v[76:77], v[80:81] op_sel_hi:[1, 0, 1]
	v_pk_fma_f32 v[86:87], v[216:217], v[70:71], v[86:87] op_sel_hi:[1, 0, 1]
	v_lshl_add_u64 v[230:231], v[50:51], 0, s[98:99]
	global_load_dwordx2 v[216:217], v[230:231], off
	v_lshl_add_u64 v[100:101], v[48:49], 0, s[18:19]
	ds_read_b128 v[70:73], v0 offset:960
	ds_read_b128 v[74:77], v0 offset:976
	ds_read2_b32 v[106:107], v95 offset0:120 offset1:144
	v_add_u32_e32 v95, 0x400, v0
	s_waitcnt vmcnt(15) lgkmcnt(2)
	v_pk_fma_f32 v[102:103], v[218:219], v[70:71], v[102:103] op_sel_hi:[1, 0, 1]
	v_pk_fma_f32 v[96:97], v[218:219], v[70:71], v[96:97] op_sel:[0, 1, 0]
	v_mov_b32_e32 v70, v73
	v_pk_fma_f32 v[78:79], v[218:219], v[70:71], v[78:79] op_sel_hi:[1, 0, 1]
	s_waitcnt lgkmcnt(1)
	v_mov_b32_e32 v70, v77
	v_pk_fma_f32 v[104:105], v[218:219], v[72:73], v[104:105] op_sel_hi:[1, 0, 1]
	v_pk_fma_f32 v[98:99], v[218:219], v[74:75], v[98:99] op_sel_hi:[1, 0, 1]
	v_pk_fma_f32 v[82:83], v[218:219], v[74:75], v[82:83] op_sel:[0, 1, 0]
	v_pk_fma_f32 v[80:81], v[218:219], v[76:77], v[80:81] op_sel_hi:[1, 0, 1]
	v_pk_fma_f32 v[84:85], v[218:219], v[70:71], v[84:85] op_sel_hi:[1, 0, 1]
	s_waitcnt lgkmcnt(0)
	v_pk_fma_f32 v[86:87], v[218:219], v[106:107], v[86:87] op_sel_hi:[1, 0, 1]
	v_lshl_add_u64 v[230:231], v[48:49], 0, s[98:99]
	global_load_dwordx2 v[218:219], v[230:231], off
	v_lshl_add_u64 v[100:101], v[46:47], 0, s[18:19]
	ds_read_b128 v[70:73], v0 offset:1056
	ds_read_b128 v[74:77], v0 offset:1072
	s_waitcnt vmcnt(15) lgkmcnt(1)
	v_pk_fma_f32 v[102:103], v[220:221], v[70:71], v[102:103] op_sel_hi:[1, 0, 1]
	v_pk_fma_f32 v[96:97], v[220:221], v[70:71], v[96:97] op_sel:[0, 1, 0]
	v_mov_b32_e32 v70, v73
	v_pk_fma_f32 v[78:79], v[220:221], v[70:71], v[78:79] op_sel_hi:[1, 0, 1]
	s_waitcnt lgkmcnt(0)
	v_mov_b32_e32 v70, v77
	v_pk_fma_f32 v[84:85], v[220:221], v[70:71], v[84:85] op_sel_hi:[1, 0, 1]
	v_mov_b32_e32 v70, v107
	v_pk_fma_f32 v[104:105], v[220:221], v[72:73], v[104:105] op_sel_hi:[1, 0, 1]
	v_pk_fma_f32 v[98:99], v[220:221], v[74:75], v[98:99] op_sel_hi:[1, 0, 1]
	v_pk_fma_f32 v[82:83], v[220:221], v[74:75], v[82:83] op_sel:[0, 1, 0]
	v_pk_fma_f32 v[80:81], v[220:221], v[76:77], v[80:81] op_sel_hi:[1, 0, 1]
	v_pk_fma_f32 v[86:87], v[220:221], v[70:71], v[86:87] op_sel_hi:[1, 0, 1]
	v_lshl_add_u64 v[230:231], v[46:47], 0, s[98:99]
	global_load_dwordx2 v[220:221], v[230:231], off
	v_lshl_add_u64 v[100:101], v[44:45], 0, s[18:19]
	ds_read_b128 v[70:73], v0 offset:1152
	ds_read_b128 v[74:77], v0 offset:1168
	ds_read2_b32 v[106:107], v95 offset0:40 offset1:64
	s_waitcnt vmcnt(15) lgkmcnt(2)
	v_pk_fma_f32 v[102:103], v[222:223], v[70:71], v[102:103] op_sel_hi:[1, 0, 1]
	v_pk_fma_f32 v[96:97], v[222:223], v[70:71], v[96:97] op_sel:[0, 1, 0]
	v_mov_b32_e32 v70, v73
	v_pk_fma_f32 v[78:79], v[222:223], v[70:71], v[78:79] op_sel_hi:[1, 0, 1]
	s_waitcnt lgkmcnt(1)
	v_mov_b32_e32 v70, v77
	v_pk_fma_f32 v[104:105], v[222:223], v[72:73], v[104:105] op_sel_hi:[1, 0, 1]
	v_pk_fma_f32 v[98:99], v[222:223], v[74:75], v[98:99] op_sel_hi:[1, 0, 1]
	v_pk_fma_f32 v[82:83], v[222:223], v[74:75], v[82:83] op_sel:[0, 1, 0]
	v_pk_fma_f32 v[80:81], v[222:223], v[76:77], v[80:81] op_sel_hi:[1, 0, 1]
	v_pk_fma_f32 v[84:85], v[222:223], v[70:71], v[84:85] op_sel_hi:[1, 0, 1]
	s_waitcnt lgkmcnt(0)
	v_pk_fma_f32 v[86:87], v[222:223], v[106:107], v[86:87] op_sel_hi:[1, 0, 1]
	v_lshl_add_u64 v[230:231], v[44:45], 0, s[98:99]
	global_load_dwordx2 v[222:223], v[230:231], off
	v_lshl_add_u64 v[100:101], v[42:43], 0, s[18:19]
	ds_read_b128 v[70:73], v0 offset:1248
	ds_read_b128 v[74:77], v0 offset:1264
	s_waitcnt vmcnt(15) lgkmcnt(1)
	v_pk_fma_f32 v[102:103], v[224:225], v[70:71], v[102:103] op_sel_hi:[1, 0, 1]
	v_pk_fma_f32 v[96:97], v[224:225], v[70:71], v[96:97] op_sel:[0, 1, 0]
	v_mov_b32_e32 v70, v73
	v_pk_fma_f32 v[78:79], v[224:225], v[70:71], v[78:79] op_sel_hi:[1, 0, 1]
	s_waitcnt lgkmcnt(0)
	v_mov_b32_e32 v70, v77
	v_pk_fma_f32 v[84:85], v[224:225], v[70:71], v[84:85] op_sel_hi:[1, 0, 1]
	v_mov_b32_e32 v70, v107
	v_pk_fma_f32 v[104:105], v[224:225], v[72:73], v[104:105] op_sel_hi:[1, 0, 1]
	v_pk_fma_f32 v[98:99], v[224:225], v[74:75], v[98:99] op_sel_hi:[1, 0, 1]
	v_pk_fma_f32 v[82:83], v[224:225], v[74:75], v[82:83] op_sel:[0, 1, 0]
	v_pk_fma_f32 v[80:81], v[224:225], v[76:77], v[80:81] op_sel_hi:[1, 0, 1]
	v_pk_fma_f32 v[86:87], v[224:225], v[70:71], v[86:87] op_sel_hi:[1, 0, 1]
	v_lshl_add_u64 v[230:231], v[42:43], 0, s[98:99]
	global_load_dwordx2 v[224:225], v[230:231], off
	v_lshl_add_u64 v[100:101], v[40:41], 0, s[18:19]
	ds_read_b128 v[70:73], v0 offset:1344
	ds_read_b128 v[74:77], v0 offset:1360
	ds_read2_b32 v[106:107], v95 offset0:88 offset1:112
	s_waitcnt vmcnt(15) lgkmcnt(2)
	v_pk_fma_f32 v[102:103], v[226:227], v[70:71], v[102:103] op_sel_hi:[1, 0, 1]
	v_pk_fma_f32 v[96:97], v[226:227], v[70:71], v[96:97] op_sel:[0, 1, 0]
	v_mov_b32_e32 v70, v73
	v_pk_fma_f32 v[78:79], v[226:227], v[70:71], v[78:79] op_sel_hi:[1, 0, 1]
	s_waitcnt lgkmcnt(1)
	v_mov_b32_e32 v70, v77
	v_pk_fma_f32 v[110:111], v[226:227], v[70:71], v[84:85] op_sel_hi:[1, 0, 1]
	v_lshl_add_u64 v[70:71], v[38:39], 0, s[18:19]
	v_pk_fma_f32 v[104:105], v[226:227], v[72:73], v[104:105] op_sel_hi:[1, 0, 1]
	v_pk_fma_f32 v[98:99], v[226:227], v[74:75], v[98:99] op_sel_hi:[1, 0, 1]
	v_pk_fma_f32 v[108:109], v[226:227], v[74:75], v[82:83] op_sel:[0, 1, 0]
	v_pk_fma_f32 v[80:81], v[226:227], v[76:77], v[80:81] op_sel_hi:[1, 0, 1]
	s_waitcnt lgkmcnt(0)
	v_pk_fma_f32 v[86:87], v[226:227], v[106:107], v[86:87] op_sel_hi:[1, 0, 1]
	v_lshl_add_u64 v[230:231], v[40:41], 0, s[98:99]
	global_load_dwordx2 v[226:227], v[230:231], off
	ds_read_b128 v[74:77], v0 offset:1440
	ds_read_b128 v[82:85], v0 offset:1456
	s_add_u32 s18, s18, 0xc0000
	s_addc_u32 s19, s19, 0
	v_add_u32_e32 v0, 0x600, v0
	s_cmp_eq_u32 s18, 0x300000
	s_waitcnt vmcnt(15) lgkmcnt(1)
	v_pk_fma_f32 v[70:71], v[228:229], v[74:75], v[102:103] op_sel_hi:[1, 0, 1]
	v_pk_fma_f32 v[74:75], v[228:229], v[74:75], v[96:97] op_sel:[0, 1, 0]
	v_pk_fma_f32 v[72:73], v[228:229], v[76:77], v[104:105] op_sel_hi:[1, 0, 1]
	v_mov_b32_e32 v76, v77
	s_waitcnt lgkmcnt(0)
	v_pk_fma_f32 v[80:81], v[228:229], v[84:85], v[80:81] op_sel_hi:[1, 0, 1]
	v_mov_b32_e32 v84, v85
	v_mov_b32_e32 v96, v107
	v_pk_fma_f32 v[78:79], v[228:229], v[76:77], v[78:79] op_sel_hi:[1, 0, 1]
	v_pk_fma_f32 v[76:77], v[228:229], v[82:83], v[98:99] op_sel_hi:[1, 0, 1]
	v_pk_fma_f32 v[82:83], v[228:229], v[82:83], v[108:109] op_sel:[0, 1, 0]
	v_pk_fma_f32 v[84:85], v[228:229], v[84:85], v[110:111] op_sel_hi:[1, 0, 1]
	v_pk_fma_f32 v[86:87], v[228:229], v[96:97], v[86:87] op_sel_hi:[1, 0, 1]
	v_lshl_add_u64 v[230:231], v[38:39], 0, s[98:99]
	global_load_dwordx2 v[228:229], v[230:231], off
	s_cbranch_scc0 .LBB0_1335
	v_add_u32_e32 v0, 0xc000, v93
	ds_write2_b64 v0, v[70:71], v[74:75] offset1:32
	ds_write2_b64 v0, v[72:73], v[78:79] offset0:64 offset1:96
	ds_write2_b64 v0, v[76:77], v[82:83] offset0:128 offset1:160
	ds_write2_b64 v0, v[80:81], v[84:85] offset0:192 offset1:224
	ds_write_b64 v93, v[86:87] offset:51200
	s_waitcnt lgkmcnt(0)
	s_barrier
	s_and_saveexec_b64 s[16:17], s[6:7]
	s_cbranch_execz .LBB0_1324
	s_mul_i32 s15, s20, 0x1800
	s_add_i32 s15, s15, s14
	v_or_b32_e32 v38, s15, v131
	v_mad_u64_u32 v[40:41], s[14:15], s20, 9, v[130:131]
	v_mov_b64_e32 v[42:43], s[0:1]
	v_ashrrev_i32_e32 v39, 31, v38
	v_mad_i64_i32 v[40:41], s[0:1], v40, s35, v[42:43]
	v_lshl_add_u64 v[38:39], v[38:39], 2, s[62:63]
	v_lshl_add_u64 v[40:41], v[36:37], 0, v[40:41]
	s_mov_b64 s[0:1], 0
	v_mov_b32_e32 v0, v92
	v_mov_b32_e32 v42, v91
